# S5-out phase: static priority 1 for waves 4-7 (on top of the attention priority split)
# baseline (speedup 1.0000x reference)
; #define GAS __attribute__((address_space(1)))
; #define LAS __attribute__((address_space(3)))
; __device__ __forceinline__ v4u pack8(const float* x) { v4u w; w.x = pk2(x[0], x[1]); w.y = pk2(x[2], x[3]); w.z = pk2(x[4], x[5]); w.w = pk2(x[6], x[7]); return w; }
; __device__ __forceinline__ unsigned char* ws_(const Frame& F) { return (unsigned char*)inp(F, 31); }
; __device__ __forceinline__ void ph_s5_out(Frame& F) {
;     LAS unsigned char* L = F.lds + RING_OFF;
;     const int lane = F.lane, r32 = lane & 31, hh = lane >> 5, wave = F.wave, tid = F.tid;
;     unsigned char* ws = ws_(F);
;     for (int u = F.vcu; u < 288; u += F.G) {
;         const int g = u / 9, nb = u % 9; int chunk = nb * 32 + r32; const bool valid = chunk < NCH; if (!valid) chunk = NCH - 1;
;         __syncthreads();
;         { const GAS v4u* tp = (const GAS v4u*)((const bf16*)(ws + WS_TOEP) + (size_t)g * 127 * 256); const float* t0 = (const float*)(ws + WS_T0) + (size_t)g * 512;
;           for (int c = tid; c < 127 * 32; c += 512) { const int di = c >> 5, p = (c >> 1) & 15, half = c & 1; v4u v;
;               if (di == 63) { float o[8];
; #pragma unroll
;                   for (int j = 0; j < 8; ++j) o[j] = t0[p * 16 + half * 8 + j] + t0[256 + p * 16 + half * 8 + j];
;                   v = pack8(o); }
;               else v = tp[c];
;               *(LAS v4u*)(L + (di * 16 + p) * TP_PITCH + half * 16) = v; } }
;         __syncthreads();
;         const bf16* ub = ug_frag_base(ws, g, nb, lane);
;         f32x16 acc[4];
; #pragma unroll
;         for (int i = 0; i < 4; ++i)
; #pragma unroll
;             for (int r = 0; r < 16; ++r) acc[i][r] = 0.f;
;         const LAS unsigned char* tl = L + ((63 + 2 * wave + (r32 >> 4)) * 16 + (r32 & 15)) * TP_PITCH + hh * 16;
; #pragma unroll 1
.LBB0_961:
	v_ashrrev_i32_e32 v4, 5, v234
	v_and_b32_e32 v1, 31, v234
	s_andn2_b64 vcc, exec, s[2:3]
	v_lshlrev_b32_e32 v73, 4, v4
	v_lshlrev_b32_e32 v188, 2, v4
	v_lshlrev_b32_e32 v66, 3, v4
	s_cbranch_vccnz .LBB0_978
	v_readfirstlane_b32 s99, v236
	s_lshr_b32 s99, s99, 8
	s_cmp_lg_u32 s99, 0
	s_cbranch_scc0 .Ls5_prio_done
	s_setprio 1
.Ls5_prio_done:
	s_add_u32 s36, s20, 0xab00000
	v_readlane_b32 s4, v254, 5
	s_addc_u32 s37, s21, 0
	s_lshl_b32 s33, s4, 5
	v_readlane_b32 s5, v254, 6
	s_mov_b32 s24, s4
	s_add_i32 s4, s33, 0x3f0
	s_mov_b32 s25, 0
	v_and_b32_e32 v4, 1, v236
	v_ashrrev_i32_e32 v235, 31, v234
	v_add_u32_e32 v6, s4, v1
	s_lshl_b64 s[22:23], s[24:25], 14
	s_lshl_b32 s4, s24, 1
	v_lshlrev_b32_e32 v8, 3, v4
	v_lshl_add_u32 v72, v4, 4, 0
	s_mov_b32 s5, s25
	v_add_u32_e32 v4, 32, v73
	s_mov_b32 s7, s25
	s_mov_b32 s9, s25
	s_mov_b32 s11, s25
	s_mov_b32 s13, s25
	s_mov_b32 s15, s25
	s_mov_b32 s17, s25
	v_writelane_b32 v254, s24, 5
	v_ashrrev_i32_e32 v237, 31, v236
	v_lshlrev_b64 v[2:3], 4, v[234:235]
	v_and_b32_e32 v90, 0xffffffe0, v4
	v_writelane_b32 v254, s25, 6
	s_mov_b32 s19, s25
	v_lshl_add_u64 v[4:5], v[236:237], 4, s[20:21]
	s_mov_b64 s[24:25], 0xa900000
	s_add_u32 s38, s20, 0xba00000
	v_lshl_add_u64 v[74:75], v[4:5], 0, s[24:25]
	v_lshl_add_u64 v[4:5], s[20:21], 0, v[2:3]
	s_mov_b64 s[24:25], 0x3c00
	v_and_b32_e32 v68, 8, v66
	v_mov_b32_e32 v69, 0
	s_addc_u32 s39, s21, 0
	s_or_b32 s6, s4, 1
	s_add_i32 s8, s4, 16
	s_add_i32 s10, s4, 17
	s_add_i32 s12, s4, 32
	s_add_i32 s14, s4, 33
	s_add_i32 s16, s4, 48
	s_add_i32 s18, s4, 49
	v_lshl_add_u64 v[76:77], v[4:5], 0, s[24:25]
	v_lshrrev_b32_e32 v6, 4, v6
	s_movk_i32 s24, 0x300
	v_and_b32_e32 v7, 15, v234
	v_lshl_add_u64 v[70:71], s[20:21], 0, v[68:69]
	v_mul_lo_u32 v6, v6, s24
	s_add_u32 s20, s20, s22
	v_mad_u32_u24 v6, v7, 48, v6
	s_addc_u32 s21, s21, s23
	s_movk_i32 s2, 0xfe0
	v_add3_u32 v6, v6, v73, 0
	v_lshl_add_u64 v[78:79], s[20:21], 0, v[2:3]
	s_mov_b64 s[20:21], 0xb500800
	v_cmp_gt_i32_e64 s[2:3], s2, v236
	v_and_b32_e32 v67, 0xffffffe0, v73
	v_ashrrev_i32_e32 v189, 31, v188
	v_add_u32_e32 v91, 0xffffd300, v6
	v_lshl_add_u64 v[80:81], v[4:5], 0, s[20:21]
	v_lshlrev_b32_e32 v92, 2, v8
	s_mov_b64 s[20:21], 0x2000
	s_movk_i32 s40, 0xddf
	s_mov_b32 s41, 0x6f00000
	s_movk_i32 s42, 0xd000
	s_movk_i32 s43, 0xe000
	s_movk_i32 s44, 0xf000
	s_mov_b64 s[22:23], 0x4000
	s_movk_i32 s45, 0x108
	s_add_i32 s46, 0, 0x204c0
	s_movk_i32 s47, 0x100
	v_mov_b32_e32 v93, 0xfe00
	v_mov_b32_e32 v94, 0xdc00000
	v_mov_b32_e32 v95, 0x6f00000
	s_mov_b32 s48, s77
	s_branch .LBB0_964

; #define LAS __attribute__((address_space(3)))
; __device__ __forceinline__ unsigned char* ws_(const Frame& F) { return (unsigned char*)inp(F, 31); }
; __device__ __forceinline__ void ph_s5_out(Frame& F) {
;     ...
;     for (int u = F.vcu; u < 288; u += F.G) {
; __device__ __forceinline__ void ph_attn(Frame& F) {
;     LAS unsigned char* L = F.lds + RING_OFF;
;     const int lane = F.lane, r32 = lane & 31, hi = lane >> 5, wave = F.wave;
;     volatile LAS float* wsf = (volatile LAS float*)(L + AT_WS) + wave * 32;
;     const bf16* Qb = (const bf16*)(ws_(F) + WS_QB); const bf16* Kb = (const bf16*)(ws_(F) + WS_KB); const bf16* Vt = (const bf16*)(ws_(F) + WS_VB);
.LBB0_977:
	s_setprio 0
	s_add_i32 s2, 0, 0x204f8
	s_nop 1
	v_mov_b32_e32 v2, s2
	ds_read_b64 v[2:3], v2
